# GEMM1 on workgroups 0-230 in 7 rounds including the 80 formerly deferred units (P4 becomes hgrn-only on 256 workgroups); workgroups 231-255 convert the later-needed weights during GEMM1
# speedup vs baseline: 1.0187x; 1.0064x over previous
.LBB0_248:
.LBB0_249:
	s_cmp_lt_i32 s86, 2
	s_cselect_b64 s[2:3], -1, 0
	s_add_u32 s62, s84, 0xb000000
	s_addc_u32 s63, s85, 0
	s_add_u32 s64, s84, 0xf800000
	s_addc_u32 s65, s85, 0
	s_add_u32 s70, s84, 0x13800000
	s_addc_u32 s71, s85, 0
	s_add_u32 s4, s84, 0x17800000
	s_addc_u32 s5, s85, 0
	s_and_b64 s[0:1], s[2:3], s[0:1]
	v_writelane_b32 v228, s4, 14
	s_andn2_b64 vcc, exec, s[0:1]
	s_nop 0
	v_writelane_b32 v228, s5, 15
	s_cbranch_vccnz .LBB0_392
	s_cmp_lg_u32 s88, 0x100
	s_cbranch_scc1 .Lp1_all
	s_cmp_lt_u32 s94, 0xe7
	s_cbranch_scc1 .Lp1_gemm
	v_readlane_b32 s0, v228, 12
	v_readlane_b32 s1, v228, 13
	s_sub_u32 s0, s0, 0xb0
	s_subb_u32 s1, s1, 0
	s_load_dwordx16 s[60:75], s[0:1], 0x0
	s_load_dwordx4 s[76:79], s[0:1], 0x80
	s_add_i32 s94, s94, 25
	s_movk_i32 s88, 100
	s_mov_b32 s101, 2
	s_movk_i32 s99, 0x39ff
	s_movk_i32 s100, 0x1b00
	s_waitcnt lgkmcnt(0)
	s_branch .Lp0_entry
.Lp1_conv_ret:
	s_sub_i32 s94, s94, 25
	v_readlane_b32 s88, v228, 6
	s_mov_b32 s101, 0
	s_add_u32 s62, s84, 0xb000000
	s_addc_u32 s63, s85, 0
	s_add_u32 s64, s84, 0xf800000
	s_addc_u32 s65, s85, 0
	s_add_u32 s70, s84, 0x13800000
	s_addc_u32 s71, s85, 0
	s_add_u32 s4, s84, 0x17800000
	s_addc_u32 s5, s85, 0
	s_nop 0
	v_writelane_b32 v228, s94, 16
	v_writelane_b32 v228, s4, 14
	v_writelane_b32 v228, s5, 15
	s_waitcnt vmcnt(0) lgkmcnt(0)
	s_barrier
	s_mov_b64 s[0:1], -1
	s_branch .LBB0_392
.Lp1_gemm:
	s_movk_i32 s88, 0xe7

.LBB0_266:
	s_add_i32 s41, s41, 1
	s_cmp_ge_i32 s41, s35
	s_cbranch_scc0 .LBB0_268
	s_cmp_lg_u32 s88, 0xe7
	s_cbranch_scc1 .Lp1_nodef
	s_cmp_lg_u32 s41, s35
	s_cbranch_scc1 .Lp1_nodef
	s_sub_i32 s12, s94, 0x96
	s_cmp_lt_u32 s12, 0x50
	s_cbranch_scc0 .Lp1_nodef
	s_cmp_lt_u32 s12, 0x40
	s_cbranch_scc0 .Lp1_defkv
	s_and_b32 s14, s12, 1
	s_add_i32 s14, s14, 48
	s_lshr_b32 s12, s12, 1
	s_branch .LBB0_275
.Lp1_defkv:
	s_sub_i32 s12, s12, 0x40
	s_and_b32 s14, s12, 3
	s_add_i32 s14, s14, 50
	s_lshr_b32 s12, s12, 2
	s_add_i32 s12, s12, 32
	s_branch .LBB0_275
.Lp1_nodef:
	s_cmp_eq_u32 s41, s35
	s_cselect_b64 s[20:21], -1, 0
	s_and_b64 s[20:21], s[20:21], s[4:5]
	s_mov_b32 s2, s46
	s_cbranch_execz .LBB0_269
	s_branch .LBB0_270

.LBB0_687:
	s_cmp_lt_i32 s86, 5
	s_cselect_b64 s[2:3], -1, 0
	s_and_b64 s[0:1], s[2:3], s[0:1]
	v_writelane_b32 v228, s0, 18
	s_andn2_b64 vcc, exec, s[0:1]
	s_nop 0
	v_writelane_b32 v228, s1, 19
	s_cbranch_vccnz .LBB0_758
	s_cmpk_lt_i32 s88, 0xa0
	s_cselect_b64 s[10:11], -1, 0
	s_and_b64 s[0:1], s[10:11], exec
	s_cselect_b32 s3, 0, 0x50
	s_cmp_eq_u32 s88, 0x100
	s_cselect_b32 s3, 0, s3
	s_cmp_lt_i32 s94, s3
	s_cselect_b64 s[0:1], -1, 0
	s_or_b64 s[4:5], s[10:11], s[0:1]
	v_and_b32_e32 v131, 63, v165
	v_and_b32_e32 v148, 15, v165
	v_lshrrev_b32_e32 v151, 2, v165
	v_lshrrev_b32_e32 v150, 3, v165
	v_bfe_u32 v149, v165, 4, 2
	s_andn2_b64 vcc, exec, s[4:5]
	v_and_b32_e32 v130, 48, v165
	s_cbranch_vccnz .LBB0_748
	s_add_u32 s2, s84, 0x200000
	s_addc_u32 s28, s85, 0
	s_cmpk_lt_i32 s94, 0x50
	s_cselect_b64 s[6:7], -1, 0
	s_cmpk_gt_i32 s94, 0x4f
	v_readfirstlane_b32 s12, v165
	s_cbranch_scc1 .LBB0_691
	s_sub_i32 s4, s94, 64
	s_lshr_b32 s4, s4, 2
	s_and_b32 s5, s94, 3
	s_and_b32 s9, s94, 1
	s_add_i32 s4, s4, 32
	s_add_i32 s5, s5, 50
	s_ashr_i32 s8, s94, 1
	s_or_b32 s9, s9, 48
	s_cmp_lt_i32 s94, 64
	s_cselect_b32 s4, s8, s4
	s_cselect_b32 s44, s9, s5
	s_ashr_i32 s5, s4, 31
	s_lshl_b64 s[8:9], s[4:5], 20
	s_add_u32 s22, s56, s8
	s_addc_u32 s23, s57, s9
	s_lshl_b32 s5, s44, 20
	s_add_u32 s24, s2, s5
	s_addc_u32 s25, s28, 0
	s_andn2_b64 vcc, exec, s[6:7]
	s_cbranch_vccz .LBB0_692
	s_branch .LBB0_747
